# GEMM K-loop (FFN-up, in-proj): one A-tile LDS-DMA stage moved from the 3-stage phase to the 1-stage phase, counted waits 8 to 6
# speedup vs baseline: 1.0050x; 1.0050x over previous
; #define PG8_STAGE(bufoff, gbase) do { _Pragma("unroll") for (int _i = 0; _i < 2; ++_i) \
;         __builtin_amdgcn_global_load_lds((const unsigned*)((const char*)(gbase) + voffA[_i]), (LAS unsigned*)(lds + (bufoff) + ldsw + _i * 8192), 16, 0, 0); } while (0)
; #define PG8_LDA(dst, b, h) do { _Pragma("unroll") for (int m = 0; m < 4; ++m) _Pragma("unroll") for (int k = 0; k < 2; ++k) dst[m][k] = *(const LAS bf16x8*)(lds + PG8_SA(b, h) + aoff + m * 2048 + k * 1024); } while (0)
; #define PG8_LDB(dst, b, h) do { _Pragma("unroll") for (int n = 0; n < 2; ++n) _Pragma("unroll") for (int k = 0; k < 2; ++k) dst[n][k] = *(const LAS bf16x8*)(lds + PG8_SB(b, h) + boff + n * 2048 + k * 1024); } while (0)
; #define PG8_MMA(ai, bj, At, Bt) do { __builtin_amdgcn_s_setprio(1); _Pragma("unroll") for (int m = 0; m < 4; ++m) _Pragma("unroll") for (int n = 0; n < 2; ++n) _Pragma("unroll") for (int k = 0; k < 2; ++k) \
;         acc[ai][bj][m][n] = __builtin_amdgcn_mfma_f32_16x16x32_bf16(Bt[n][k], At[m][k], acc[ai][bj][m][n], 0, 0, 0); __builtin_amdgcn_s_setprio(0); } while (0)
; #define PG8_WAIT_V(n) asm volatile("s_waitcnt vmcnt(" #n ")" ::: "memory")
; #define PG8_WAIT_L(n) asm volatile("s_waitcnt lgkmcnt(" #n ")" ::: "memory")
; #define PG8_BAR __builtin_amdgcn_s_barrier()
; #define PG8_SCHED __builtin_amdgcn_sched_barrier(0)
; template <class Epi, class Sched>
; __device__ __forceinline__ void gemm_phase(LAS unsigned char* lds, const Gemm g, const Sched& S, const Epi& E) {
;     ...
;         for (int t = 0; t < nt; t += 2) {
;             const bool last = (t == nt - 2);
;             const char* a1 = cA + (size_t)(t + 1) * kstep;
;             const char* a2 = last ? nA : cA + (size_t)(t + 2) * kstep; const char* b2 = last ? nB : cB + (size_t)(t + 2) * kstep;
;             const char* a3 = a2 + kstep; const char* b3 = b2 + kstep;
;             PG8_LDB(B0, 0, 0); PG8_LDB(B1, 0, 1); PG8_SCHED; PG8_LDA(At, 0, 0); PG8_STAGE(PG8_SA(1, 1), a1 + hstep);
;             PG8_WAIT_V(8); PG8_WAIT_L(0); PG8_BAR; PG8_MMA(0, 0, At, B0); PG8_MMA(0, 1, At, B1); PG8_BAR; PG8_SCHED;
;             PG8_LDA(At, 0, 1); PG8_STAGE(PG8_SB(0, 0), b2); PG8_STAGE(PG8_SB(0, 1), b2 + hstep); PG8_STAGE(PG8_SA(0, 0), a2);
;             PG8_WAIT_V(8); PG8_WAIT_L(0); PG8_BAR; PG8_MMA(1, 0, At, B0); PG8_MMA(1, 1, At, B1); PG8_BAR; PG8_SCHED;
.LBB0_51:
	s_add_u32 s64, s62, 0xfff80080
	s_addc_u32 s65, s63, -1
	s_add_i32 s91, 0, 0x10000
	s_cmp_eq_u32 s90, 28
	s_cselect_b32 s67, s47, s65
	s_cselect_b32 s66, s84, s64
	v_add_u32_e32 v136, s91, v139
	s_cselect_b32 s65, s45, s89
	s_cselect_b32 s64, s85, s88
	s_add_i32 s94, 0, 0x14000
	ds_read_b128 v[142:145], v136
	ds_read_b128 v[164:167], v136 offset:1024
	ds_read_b128 v[168:171], v136 offset:2048
	ds_read_b128 v[172:175], v136 offset:3072
	v_add_u32_e32 v136, s94, v139
	ds_read_b128 v[176:179], v136
	ds_read_b128 v[180:183], v136 offset:1024
	ds_read_b128 v[184:187], v136 offset:2048
	ds_read_b128 v[188:191], v136 offset:3072
	v_lshl_add_u64 v[136:137], s[62:63], 0, v[132:133]
	s_add_i32 m0, s69, 0xc000
	ds_read_b128 v[192:195], v141
	ds_read_b128 v[196:199], v141 offset:1024
	ds_read_b128 v[200:203], v141 offset:2048
	ds_read_b128 v[204:207], v141 offset:3072
	ds_read_b128 v[208:211], v141 offset:4096
	ds_read_b128 v[222:225], v141 offset:5120
	ds_read_b128 v[226:229], v141 offset:6144
	ds_read_b128 v[230:233], v141 offset:7168
	global_load_lds_dwordx4 v[136:137], off
	v_lshl_add_u64 v[136:137], s[62:63], 0, v[134:135]
	s_add_i32 m0, s69, 0xe000
	s_nop 0
	global_load_lds_dwordx4 v[136:137], off
	s_waitcnt vmcnt(8)
	s_waitcnt lgkmcnt(0)
	s_barrier
	s_setprio 1
	s_waitcnt lgkmcnt(0)
	v_mfma_f32_16x16x32_bf16 v[126:129], v[142:145], v[192:195], v[126:129]
	v_mfma_f32_16x16x32_bf16 v[118:121], v[168:171], v[192:195], v[118:121]
	v_mfma_f32_16x16x32_bf16 v[110:113], v[142:145], v[200:203], v[110:113]
	v_mfma_f32_16x16x32_bf16 v[102:105], v[168:171], v[200:203], v[102:105]
	v_mfma_f32_16x16x32_bf16 v[94:97], v[142:145], v[208:211], v[94:97]
	v_mfma_f32_16x16x32_bf16 v[86:89], v[168:171], v[208:211], v[86:89]
	v_mfma_f32_16x16x32_bf16 v[78:81], v[142:145], v[226:229], v[78:81]
	v_mfma_f32_16x16x32_bf16 v[70:73], v[168:171], v[226:229], v[70:73]
	v_mfma_f32_16x16x32_bf16 v[126:129], v[164:167], v[196:199], v[126:129]
	v_mfma_f32_16x16x32_bf16 v[118:121], v[172:175], v[196:199], v[118:121]
	v_mfma_f32_16x16x32_bf16 v[110:113], v[164:167], v[204:207], v[110:113]
	v_mfma_f32_16x16x32_bf16 v[102:105], v[172:175], v[204:207], v[102:105]
	v_mfma_f32_16x16x32_bf16 v[94:97], v[164:167], v[222:225], v[94:97]
	v_mfma_f32_16x16x32_bf16 v[86:89], v[172:175], v[222:225], v[86:89]
	v_mfma_f32_16x16x32_bf16 v[78:81], v[164:167], v[230:233], v[78:81]
	v_mfma_f32_16x16x32_bf16 v[70:73], v[172:175], v[230:233], v[70:73]
	s_setprio 0
	s_setprio 1
	v_mfma_f32_16x16x32_bf16 v[122:125], v[176:179], v[192:195], v[122:125]
	v_mfma_f32_16x16x32_bf16 v[114:117], v[184:187], v[192:195], v[114:117]
	v_mfma_f32_16x16x32_bf16 v[106:109], v[176:179], v[200:203], v[106:109]
	v_mfma_f32_16x16x32_bf16 v[98:101], v[184:187], v[200:203], v[98:101]
	v_mfma_f32_16x16x32_bf16 v[90:93], v[176:179], v[208:211], v[90:93]
	v_mfma_f32_16x16x32_bf16 v[82:85], v[184:187], v[208:211], v[82:85]
	v_mfma_f32_16x16x32_bf16 v[74:77], v[176:179], v[226:229], v[74:77]
	v_mfma_f32_16x16x32_bf16 v[66:69], v[184:187], v[226:229], v[66:69]
	v_mfma_f32_16x16x32_bf16 v[122:125], v[180:183], v[196:199], v[122:125]
	v_mfma_f32_16x16x32_bf16 v[114:117], v[188:191], v[196:199], v[114:117]
	v_mfma_f32_16x16x32_bf16 v[106:109], v[180:183], v[204:207], v[106:109]
	v_mfma_f32_16x16x32_bf16 v[98:101], v[188:191], v[204:207], v[98:101]
	v_mfma_f32_16x16x32_bf16 v[90:93], v[180:183], v[222:225], v[90:93]
	v_mfma_f32_16x16x32_bf16 v[82:85], v[188:191], v[222:225], v[82:85]
	v_mfma_f32_16x16x32_bf16 v[74:77], v[180:183], v[230:233], v[74:77]
	v_mfma_f32_16x16x32_bf16 v[66:69], v[188:191], v[230:233], v[66:69]
	s_setprio 0
	s_barrier
	s_add_i32 s91, s91, s57
	v_lshl_add_u64 v[136:137], s[64:65], 0, v[0:1]
	s_mov_b32 m0, s91
	ds_read_b128 v[192:195], v141 offset:16384
	ds_read_b128 v[196:199], v141 offset:17408
	ds_read_b128 v[200:203], v141 offset:18432
	ds_read_b128 v[204:207], v141 offset:19456
	ds_read_b128 v[208:211], v141 offset:20480
	ds_read_b128 v[222:225], v141 offset:21504
	ds_read_b128 v[226:229], v141 offset:22528
	ds_read_b128 v[230:233], v141 offset:23552
	global_load_lds_dwordx4 v[136:137], off
	s_add_i32 m0, s91, 0x2000
	s_add_u32 s92, s64, 0x80000
	v_lshl_add_u64 v[234:235], s[64:65], 0, v[130:131]
	s_addc_u32 s93, s65, 0
	s_add_i32 s91, s94, s57
	global_load_lds_dwordx4 v[234:235], off
	v_lshl_add_u64 v[236:237], s[92:93], 0, v[0:1]
	s_mov_b32 m0, s91
	v_lshl_add_u64 v[238:239], s[66:67], 0, v[130:131]
	global_load_lds_dwordx4 v[236:237], off
	v_lshl_add_u64 v[236:237], s[92:93], 0, v[130:131]
	s_add_i32 m0, s91, 0x2000
	s_nop 0
	global_load_lds_dwordx4 v[236:237], off
	v_lshl_add_u64 v[236:237], s[66:67], 0, v[0:1]
	s_waitcnt vmcnt(6)
	s_waitcnt lgkmcnt(0)
	s_barrier
; #define PG8_STAGE(bufoff, gbase) do { _Pragma("unroll") for (int _i = 0; _i < 2; ++_i) \
;         __builtin_amdgcn_global_load_lds((const unsigned*)((const char*)(gbase) + voffA[_i]), (LAS unsigned*)(lds + (bufoff) + ldsw + _i * 8192), 16, 0, 0); } while (0)
; #define PG8_LDA(dst, b, h) do { _Pragma("unroll") for (int m = 0; m < 4; ++m) _Pragma("unroll") for (int k = 0; k < 2; ++k) dst[m][k] = *(const LAS bf16x8*)(lds + PG8_SA(b, h) + aoff + m * 2048 + k * 1024); } while (0)
; #define PG8_LDB(dst, b, h) do { _Pragma("unroll") for (int n = 0; n < 2; ++n) _Pragma("unroll") for (int k = 0; k < 2; ++k) dst[n][k] = *(const LAS bf16x8*)(lds + PG8_SB(b, h) + boff + n * 2048 + k * 1024); } while (0)
; #define PG8_MMA(ai, bj, At, Bt) do { __builtin_amdgcn_s_setprio(1); _Pragma("unroll") for (int m = 0; m < 4; ++m) _Pragma("unroll") for (int n = 0; n < 2; ++n) _Pragma("unroll") for (int k = 0; k < 2; ++k) \
;         acc[ai][bj][m][n] = __builtin_amdgcn_mfma_f32_16x16x32_bf16(Bt[n][k], At[m][k], acc[ai][bj][m][n], 0, 0, 0); __builtin_amdgcn_s_setprio(0); } while (0)
; #define PG8_WAIT_V(n) asm volatile("s_waitcnt vmcnt(" #n ")" ::: "memory")
; #define PG8_WAIT_L(n) asm volatile("s_waitcnt lgkmcnt(" #n ")" ::: "memory")
; #define PG8_BAR __builtin_amdgcn_s_barrier()
; #define PG8_SCHED __builtin_amdgcn_sched_barrier(0)
; template <class Epi, class Sched>
; __device__ __forceinline__ void gemm_phase(LAS unsigned char* lds, const Gemm g, const Sched& S, const Epi& E) {
;     ...
;             PG8_WAIT_V(8); PG8_WAIT_L(0); PG8_BAR; PG8_MMA(0, 0, At, B0); PG8_MMA(0, 1, At, B1); PG8_BAR; PG8_SCHED;
;             PG8_LDA(At, 0, 1); PG8_STAGE(PG8_SB(0, 0), b2); PG8_STAGE(PG8_SB(0, 1), b2 + hstep); PG8_STAGE(PG8_SA(0, 0), a2);
;             PG8_WAIT_V(8); PG8_WAIT_L(0); PG8_BAR; PG8_MMA(1, 0, At, B0); PG8_MMA(1, 1, At, B1); PG8_BAR; PG8_SCHED;
;             PG8_LDB(B0, 1, 0); PG8_LDB(B1, 1, 1); PG8_SCHED; PG8_LDA(At, 1, 0); PG8_STAGE(PG8_SA(0, 1), a2 + hstep);
;             PG8_WAIT_V(8); PG8_WAIT_L(0); PG8_BAR; PG8_MMA(0, 0, At, B0); PG8_MMA(0, 1, At, B1); PG8_BAR; PG8_SCHED;
	s_setprio 1
	s_waitcnt lgkmcnt(0)
	v_mfma_f32_16x16x32_bf16 v[62:65], v[142:145], v[192:195], v[62:65]
	v_mfma_f32_16x16x32_bf16 v[54:57], v[168:171], v[192:195], v[54:57]
	v_mfma_f32_16x16x32_bf16 v[46:49], v[142:145], v[200:203], v[46:49]
	v_mfma_f32_16x16x32_bf16 v[38:41], v[168:171], v[200:203], v[38:41]
	v_mfma_f32_16x16x32_bf16 v[30:33], v[142:145], v[208:211], v[30:33]
	v_mfma_f32_16x16x32_bf16 v[22:25], v[168:171], v[208:211], v[22:25]
	v_mfma_f32_16x16x32_bf16 v[14:17], v[142:145], v[226:229], v[14:17]
	v_mfma_f32_16x16x32_bf16 v[6:9], v[168:171], v[226:229], v[6:9]
	v_mfma_f32_16x16x32_bf16 v[62:65], v[164:167], v[196:199], v[62:65]
	v_mfma_f32_16x16x32_bf16 v[54:57], v[172:175], v[196:199], v[54:57]
	v_mfma_f32_16x16x32_bf16 v[46:49], v[164:167], v[204:207], v[46:49]
	v_mfma_f32_16x16x32_bf16 v[38:41], v[172:175], v[204:207], v[38:41]
	v_mfma_f32_16x16x32_bf16 v[30:33], v[164:167], v[222:225], v[30:33]
	v_mfma_f32_16x16x32_bf16 v[22:25], v[172:175], v[222:225], v[22:25]
	v_mfma_f32_16x16x32_bf16 v[14:17], v[164:167], v[230:233], v[14:17]
	v_mfma_f32_16x16x32_bf16 v[6:9], v[172:175], v[230:233], v[6:9]
	s_setprio 0
	s_setprio 1
	v_mfma_f32_16x16x32_bf16 v[58:61], v[176:179], v[192:195], v[58:61]
	v_mfma_f32_16x16x32_bf16 v[50:53], v[184:187], v[192:195], v[50:53]
	v_mfma_f32_16x16x32_bf16 v[42:45], v[176:179], v[200:203], v[42:45]
	v_mfma_f32_16x16x32_bf16 v[34:37], v[184:187], v[200:203], v[34:37]
	v_mfma_f32_16x16x32_bf16 v[26:29], v[176:179], v[208:211], v[26:29]
	v_mfma_f32_16x16x32_bf16 v[18:21], v[184:187], v[208:211], v[18:21]
	v_mfma_f32_16x16x32_bf16 v[10:13], v[176:179], v[226:229], v[10:13]
	v_mfma_f32_16x16x32_bf16 v[2:5], v[184:187], v[226:229], v[2:5]
	v_mfma_f32_16x16x32_bf16 v[58:61], v[180:183], v[196:199], v[58:61]
	v_mfma_f32_16x16x32_bf16 v[50:53], v[188:191], v[196:199], v[50:53]
	v_mfma_f32_16x16x32_bf16 v[42:45], v[180:183], v[204:207], v[42:45]
	v_mfma_f32_16x16x32_bf16 v[34:37], v[188:191], v[204:207], v[34:37]
	v_mfma_f32_16x16x32_bf16 v[26:29], v[180:183], v[222:225], v[26:29]
	v_mfma_f32_16x16x32_bf16 v[18:21], v[188:191], v[222:225], v[18:21]
	v_mfma_f32_16x16x32_bf16 v[10:13], v[180:183], v[230:233], v[10:13]
	v_mfma_f32_16x16x32_bf16 v[2:5], v[188:191], v[230:233], v[2:5]
	s_setprio 0
	s_barrier
	s_add_i32 s91, 0, 0x1c000
	v_add_u32_e32 v172, s99, v139
	v_add_u32_e32 v188, s91, v139
	ds_read_b128 v[142:145], v172
	ds_read_b128 v[164:167], v172 offset:1024
	ds_read_b128 v[168:171], v172 offset:2048
	ds_read_b128 v[172:175], v172 offset:3072
	ds_read_b128 v[176:179], v188
	ds_read_b128 v[180:183], v188 offset:1024
	ds_read_b128 v[184:187], v188 offset:2048
	ds_read_b128 v[188:191], v188 offset:3072
	s_add_u32 s66, s66, 0x80000
	s_addc_u32 s67, s67, 0
	s_mov_b32 m0, s71
	v_lshl_add_u64 v[240:241], s[66:67], 0, v[0:1]
	ds_read_b128 v[192:195], v141 offset:32768
	ds_read_b128 v[196:199], v141 offset:33792
	ds_read_b128 v[200:203], v141 offset:34816
	ds_read_b128 v[204:207], v141 offset:35840
	ds_read_b128 v[208:211], v141 offset:36864
	ds_read_b128 v[222:225], v141 offset:37888
	ds_read_b128 v[226:229], v141 offset:38912
	ds_read_b128 v[230:233], v141 offset:39936
	global_load_lds_dwordx4 v[240:241], off
	v_lshl_add_u64 v[240:241], s[66:67], 0, v[130:131]
	s_mov_b32 m0, s72
	s_nop 0
	global_load_lds_dwordx4 v[240:241], off
	s_mov_b32 m0, s69
	s_nop 0
	global_load_lds_dwordx4 v[236:237], off
	s_mov_b32 m0, s70
	s_nop 0
	global_load_lds_dwordx4 v[238:239], off
	s_waitcnt vmcnt(8)
	s_waitcnt lgkmcnt(0)
	s_barrier
	s_setprio 1
	s_waitcnt lgkmcnt(0)
	v_mfma_f32_16x16x32_bf16 v[126:129], v[142:145], v[192:195], v[126:129]
	v_mfma_f32_16x16x32_bf16 v[118:121], v[168:171], v[192:195], v[118:121]
	v_mfma_f32_16x16x32_bf16 v[110:113], v[142:145], v[200:203], v[110:113]
	v_mfma_f32_16x16x32_bf16 v[102:105], v[168:171], v[200:203], v[102:105]
	v_mfma_f32_16x16x32_bf16 v[94:97], v[142:145], v[208:211], v[94:97]
	v_mfma_f32_16x16x32_bf16 v[86:89], v[168:171], v[208:211], v[86:89]
	v_mfma_f32_16x16x32_bf16 v[78:81], v[142:145], v[226:229], v[78:81]
	v_mfma_f32_16x16x32_bf16 v[70:73], v[168:171], v[226:229], v[70:73]
	v_mfma_f32_16x16x32_bf16 v[126:129], v[164:167], v[196:199], v[126:129]
	v_mfma_f32_16x16x32_bf16 v[118:121], v[172:175], v[196:199], v[118:121]
	v_mfma_f32_16x16x32_bf16 v[110:113], v[164:167], v[204:207], v[110:113]
	v_mfma_f32_16x16x32_bf16 v[102:105], v[172:175], v[204:207], v[102:105]
	v_mfma_f32_16x16x32_bf16 v[94:97], v[164:167], v[222:225], v[94:97]
	v_mfma_f32_16x16x32_bf16 v[86:89], v[172:175], v[222:225], v[86:89]
	v_mfma_f32_16x16x32_bf16 v[78:81], v[164:167], v[230:233], v[78:81]
	v_mfma_f32_16x16x32_bf16 v[70:73], v[172:175], v[230:233], v[70:73]
	s_setprio 0
	s_setprio 1
	v_mfma_f32_16x16x32_bf16 v[122:125], v[176:179], v[192:195], v[122:125]
	v_mfma_f32_16x16x32_bf16 v[114:117], v[184:187], v[192:195], v[114:117]
	v_mfma_f32_16x16x32_bf16 v[106:109], v[176:179], v[200:203], v[106:109]
	v_mfma_f32_16x16x32_bf16 v[98:101], v[184:187], v[200:203], v[98:101]
	v_mfma_f32_16x16x32_bf16 v[90:93], v[176:179], v[208:211], v[90:93]
	v_mfma_f32_16x16x32_bf16 v[82:85], v[184:187], v[208:211], v[82:85]
	v_mfma_f32_16x16x32_bf16 v[74:77], v[176:179], v[226:229], v[74:77]
	v_mfma_f32_16x16x32_bf16 v[66:69], v[184:187], v[226:229], v[66:69]
	v_mfma_f32_16x16x32_bf16 v[122:125], v[180:183], v[196:199], v[122:125]
	v_mfma_f32_16x16x32_bf16 v[114:117], v[188:191], v[196:199], v[114:117]
	v_mfma_f32_16x16x32_bf16 v[106:109], v[180:183], v[204:207], v[106:109]
	v_mfma_f32_16x16x32_bf16 v[98:101], v[188:191], v[204:207], v[98:101]
	v_mfma_f32_16x16x32_bf16 v[90:93], v[180:183], v[222:225], v[90:93]
	v_mfma_f32_16x16x32_bf16 v[82:85], v[188:191], v[222:225], v[82:85]
	v_mfma_f32_16x16x32_bf16 v[74:77], v[180:183], v[230:233], v[74:77]
	v_mfma_f32_16x16x32_bf16 v[66:69], v[188:191], v[230:233], v[66:69]
	s_setprio 0
	s_barrier
; #define PG8_STAGE(bufoff, gbase) do { _Pragma("unroll") for (int _i = 0; _i < 2; ++_i) \
;         __builtin_amdgcn_global_load_lds((const unsigned*)((const char*)(gbase) + voffA[_i]), (LAS unsigned*)(lds + (bufoff) + ldsw + _i * 8192), 16, 0, 0); } while (0)
; #define PG8_LDA(dst, b, h) do { _Pragma("unroll") for (int m = 0; m < 4; ++m) _Pragma("unroll") for (int k = 0; k < 2; ++k) dst[m][k] = *(const LAS bf16x8*)(lds + PG8_SA(b, h) + aoff + m * 2048 + k * 1024); } while (0)
; #define PG8_MMA(ai, bj, At, Bt) do { __builtin_amdgcn_s_setprio(1); _Pragma("unroll") for (int m = 0; m < 4; ++m) _Pragma("unroll") for (int n = 0; n < 2; ++n) _Pragma("unroll") for (int k = 0; k < 2; ++k) \
;         acc[ai][bj][m][n] = __builtin_amdgcn_mfma_f32_16x16x32_bf16(Bt[n][k], At[m][k], acc[ai][bj][m][n], 0, 0, 0); __builtin_amdgcn_s_setprio(0); } while (0)
; #define PG8_WAIT_V(n) asm volatile("s_waitcnt vmcnt(" #n ")" ::: "memory")
; #define PG8_WAIT_L(n) asm volatile("s_waitcnt lgkmcnt(" #n ")" ::: "memory")
; #define PG8_BAR __builtin_amdgcn_s_barrier()
; #define PG8_SCHED __builtin_amdgcn_sched_barrier(0)
; template <class Epi, class Sched>
; __device__ __forceinline__ void gemm_phase(LAS unsigned char* lds, const Gemm g, const Sched& S, const Epi& E) {
;     ...
;             PG8_LDA(At, 1, 1); PG8_STAGE(PG8_SB(1, 0), b3); PG8_STAGE(PG8_SB(1, 1), b3 + hstep); PG8_STAGE(PG8_SA(1, 0), a3);
;             PG8_WAIT_V(8); PG8_WAIT_L(0); PG8_BAR; PG8_MMA(1, 0, At, B0); PG8_MMA(1, 1, At, B1); PG8_BAR; PG8_SCHED;
;         }
	s_add_i32 s66, s99, s57
	v_lshl_add_u64 v[136:137], v[136:137], 0, s[26:27]
	s_mov_b32 m0, s66
	ds_read_b128 v[192:195], v141 offset:49152
	ds_read_b128 v[196:199], v141 offset:50176
	ds_read_b128 v[200:203], v141 offset:51200
	ds_read_b128 v[204:207], v141 offset:52224
	ds_read_b128 v[208:211], v141 offset:53248
	ds_read_b128 v[222:225], v141 offset:54272
	ds_read_b128 v[226:229], v141 offset:55296
	ds_read_b128 v[230:233], v141 offset:56320
	global_load_lds_dwordx4 v[136:137], off
	s_add_i32 m0, s66, 0x2000
	s_add_u32 s64, s64, 0x80080
	v_lshl_add_u64 v[136:137], v[234:235], 0, s[26:27]
	s_addc_u32 s65, s65, 0
	s_add_i32 s66, s91, s57
	global_load_lds_dwordx4 v[136:137], off
	v_lshl_add_u64 v[136:137], s[64:65], 0, v[0:1]
	s_mov_b32 m0, s66
	s_nop 0
	global_load_lds_dwordx4 v[136:137], off
	v_lshl_add_u64 v[136:137], s[64:65], 0, v[130:131]
	s_add_i32 m0, s66, 0x2000
	s_nop 0
	global_load_lds_dwordx4 v[136:137], off
	v_lshl_add_u64 v[136:137], v[236:237], 0, s[26:27]
	s_mov_b32 m0, s73
	s_nop 0
	global_load_lds_dwordx4 v[136:137], off
	v_lshl_add_u64 v[136:137], v[238:239], 0, s[26:27]
	s_mov_b32 m0, s74
	s_nop 0
	global_load_lds_dwordx4 v[136:137], off
	s_waitcnt vmcnt(6)
	s_waitcnt lgkmcnt(0)
	s_barrier
	s_setprio 1
	s_waitcnt lgkmcnt(0)
	v_mfma_f32_16x16x32_bf16 v[62:65], v[142:145], v[192:195], v[62:65]
	v_mfma_f32_16x16x32_bf16 v[54:57], v[168:171], v[192:195], v[54:57]
	v_mfma_f32_16x16x32_bf16 v[46:49], v[142:145], v[200:203], v[46:49]
	v_mfma_f32_16x16x32_bf16 v[38:41], v[168:171], v[200:203], v[38:41]
	v_mfma_f32_16x16x32_bf16 v[30:33], v[142:145], v[208:211], v[30:33]
	v_mfma_f32_16x16x32_bf16 v[22:25], v[168:171], v[208:211], v[22:25]
	v_mfma_f32_16x16x32_bf16 v[14:17], v[142:145], v[226:229], v[14:17]
	v_mfma_f32_16x16x32_bf16 v[6:9], v[168:171], v[226:229], v[6:9]
	v_mfma_f32_16x16x32_bf16 v[62:65], v[164:167], v[196:199], v[62:65]
	v_mfma_f32_16x16x32_bf16 v[54:57], v[172:175], v[196:199], v[54:57]
	v_mfma_f32_16x16x32_bf16 v[46:49], v[164:167], v[204:207], v[46:49]
	v_mfma_f32_16x16x32_bf16 v[38:41], v[172:175], v[204:207], v[38:41]
	v_mfma_f32_16x16x32_bf16 v[30:33], v[164:167], v[222:225], v[30:33]
	v_mfma_f32_16x16x32_bf16 v[22:25], v[172:175], v[222:225], v[22:25]
	v_mfma_f32_16x16x32_bf16 v[14:17], v[164:167], v[230:233], v[14:17]
	v_mfma_f32_16x16x32_bf16 v[6:9], v[172:175], v[230:233], v[6:9]
	s_setprio 0
	s_setprio 1
	v_mfma_f32_16x16x32_bf16 v[58:61], v[176:179], v[192:195], v[58:61]
	v_mfma_f32_16x16x32_bf16 v[50:53], v[184:187], v[192:195], v[50:53]
	v_mfma_f32_16x16x32_bf16 v[42:45], v[176:179], v[200:203], v[42:45]
	v_mfma_f32_16x16x32_bf16 v[34:37], v[184:187], v[200:203], v[34:37]
	v_mfma_f32_16x16x32_bf16 v[26:29], v[176:179], v[208:211], v[26:29]
	v_mfma_f32_16x16x32_bf16 v[18:21], v[184:187], v[208:211], v[18:21]
	v_mfma_f32_16x16x32_bf16 v[10:13], v[176:179], v[226:229], v[10:13]
	v_mfma_f32_16x16x32_bf16 v[2:5], v[184:187], v[226:229], v[2:5]
	v_mfma_f32_16x16x32_bf16 v[58:61], v[180:183], v[196:199], v[58:61]
	v_mfma_f32_16x16x32_bf16 v[50:53], v[188:191], v[196:199], v[50:53]
	v_mfma_f32_16x16x32_bf16 v[42:45], v[180:183], v[204:207], v[42:45]
	v_mfma_f32_16x16x32_bf16 v[34:37], v[188:191], v[204:207], v[34:37]
	v_mfma_f32_16x16x32_bf16 v[26:29], v[180:183], v[222:225], v[26:29]
	v_mfma_f32_16x16x32_bf16 v[18:21], v[188:191], v[222:225], v[18:21]
	v_mfma_f32_16x16x32_bf16 v[10:13], v[180:183], v[230:233], v[10:13]
	v_mfma_f32_16x16x32_bf16 v[2:5], v[188:191], v[230:233], v[2:5]
	s_setprio 0
	s_barrier
	s_add_i32 s90, s90, 2
	s_add_u32 s62, s62, 0x100
	s_addc_u32 s63, s63, 0
	s_add_u32 s88, s88, 0x100
	s_addc_u32 s89, s89, 0
	s_cmp_gt_u32 s90, 29
	s_cbranch_scc0 .LBB0_51
	s_and_b64 vcc, exec, s[20:21]
	s_cbranch_vccz .LBB0_54
	s_barrier

; #define PG8_STAGE(bufoff, gbase) do { _Pragma("unroll") for (int _i = 0; _i < 2; ++_i) \
;         __builtin_amdgcn_global_load_lds((const unsigned*)((const char*)(gbase) + voffA[_i]), (LAS unsigned*)(lds + (bufoff) + ldsw + _i * 8192), 16, 0, 0); } while (0)
; #define PG8_LDA(dst, b, h) do { _Pragma("unroll") for (int m = 0; m < 4; ++m) _Pragma("unroll") for (int k = 0; k < 2; ++k) dst[m][k] = *(const LAS bf16x8*)(lds + PG8_SA(b, h) + aoff + m * 2048 + k * 1024); } while (0)
; #define PG8_LDB(dst, b, h) do { _Pragma("unroll") for (int n = 0; n < 2; ++n) _Pragma("unroll") for (int k = 0; k < 2; ++k) dst[n][k] = *(const LAS bf16x8*)(lds + PG8_SB(b, h) + boff + n * 2048 + k * 1024); } while (0)
; #define PG8_MMA(ai, bj, At, Bt) do { __builtin_amdgcn_s_setprio(1); _Pragma("unroll") for (int m = 0; m < 4; ++m) _Pragma("unroll") for (int n = 0; n < 2; ++n) _Pragma("unroll") for (int k = 0; k < 2; ++k) \
;         acc[ai][bj][m][n] = __builtin_amdgcn_mfma_f32_16x16x32_bf16(Bt[n][k], At[m][k], acc[ai][bj][m][n], 0, 0, 0); __builtin_amdgcn_s_setprio(0); } while (0)
; #define PG8_WAIT_V(n) asm volatile("s_waitcnt vmcnt(" #n ")" ::: "memory")
; #define PG8_WAIT_L(n) asm volatile("s_waitcnt lgkmcnt(" #n ")" ::: "memory")
; #define PG8_BAR __builtin_amdgcn_s_barrier()
; #define PG8_SCHED __builtin_amdgcn_sched_barrier(0)
; template <class Epi, class Sched>
; __device__ __forceinline__ void gemm_phase(LAS unsigned char* lds, const Gemm g, const Sched& S, const Epi& E) {
;     ...
;         for (int t = 0; t < nt; t += 2) {
;             const bool last = (t == nt - 2);
;             const char* a1 = cA + (size_t)(t + 1) * kstep;
;             const char* a2 = last ? nA : cA + (size_t)(t + 2) * kstep; const char* b2 = last ? nB : cB + (size_t)(t + 2) * kstep;
;             const char* a3 = a2 + kstep; const char* b3 = b2 + kstep;
;             PG8_LDB(B0, 0, 0); PG8_LDB(B1, 0, 1); PG8_SCHED; PG8_LDA(At, 0, 0); PG8_STAGE(PG8_SA(1, 1), a1 + hstep);
;             PG8_WAIT_V(8); PG8_WAIT_L(0); PG8_BAR; PG8_MMA(0, 0, At, B0); PG8_MMA(0, 1, At, B1); PG8_BAR; PG8_SCHED;
;             PG8_LDA(At, 0, 1); PG8_STAGE(PG8_SB(0, 0), b2); PG8_STAGE(PG8_SB(0, 1), b2 + hstep); PG8_STAGE(PG8_SA(0, 0), a2);
;             PG8_WAIT_V(8); PG8_WAIT_L(0); PG8_BAR; PG8_MMA(1, 0, At, B0); PG8_MMA(1, 1, At, B1); PG8_BAR; PG8_SCHED;
.LBB0_156:
	s_add_u32 s70, s68, 0xfff80080
	s_addc_u32 s71, s69, -1
	s_add_i32 s92, 0, 0x10000
	s_cmp_eq_u32 s91, 28
	s_cselect_b32 s73, s51, s71
	s_cselect_b32 s72, s67, s70
	v_add_u32_e32 v0, s92, v170
	s_cselect_b32 s71, s49, s90
	s_cselect_b32 s70, s88, s89
	s_add_i32 s94, 0, 0x14000
	ds_read_b128 v[166:169], v0
	ds_read_b128 v[174:177], v0 offset:1024
	ds_read_b128 v[178:181], v0 offset:2048
	ds_read_b128 v[182:185], v0 offset:3072
	v_add_u32_e32 v0, s94, v170
	ds_read_b128 v[186:189], v0
	ds_read_b128 v[190:193], v0 offset:1024
	ds_read_b128 v[194:197], v0 offset:2048
	ds_read_b128 v[198:201], v0 offset:3072
	v_lshl_add_u64 v[210:211], s[68:69], 0, v[138:139]
	s_add_i32 m0, s60, 0xc000
	ds_read_b128 v[202:205], v171
	ds_read_b128 v[206:209], v171 offset:1024
	ds_read_b128 v[222:225], v171 offset:2048
	ds_read_b128 v[226:229], v171 offset:3072
	ds_read_b128 v[230:233], v171 offset:4096
	ds_read_b128 v[234:237], v171 offset:5120
	ds_read_b128 v[238:241], v171 offset:6144
	ds_read_b128 v[242:245], v171 offset:7168
	global_load_lds_dwordx4 v[210:211], off
	v_lshl_add_u64 v[210:211], s[68:69], 0, v[140:141]
	s_add_i32 m0, s60, 0xe000
	s_nop 0
	global_load_lds_dwordx4 v[210:211], off
	s_waitcnt vmcnt(8)
	s_waitcnt lgkmcnt(0)
	s_barrier
	s_setprio 1
	s_waitcnt lgkmcnt(0)
	v_mfma_f32_16x16x32_bf16 v[126:129], v[166:169], v[202:205], v[126:129]
	v_mfma_f32_16x16x32_bf16 v[122:125], v[178:181], v[202:205], v[122:125]
	v_mfma_f32_16x16x32_bf16 v[110:113], v[166:169], v[222:225], v[110:113]
	v_mfma_f32_16x16x32_bf16 v[106:109], v[178:181], v[222:225], v[106:109]
	v_mfma_f32_16x16x32_bf16 v[94:97], v[166:169], v[230:233], v[94:97]
	v_mfma_f32_16x16x32_bf16 v[90:93], v[178:181], v[230:233], v[90:93]
	v_mfma_f32_16x16x32_bf16 v[78:81], v[166:169], v[238:241], v[78:81]
	v_mfma_f32_16x16x32_bf16 v[74:77], v[178:181], v[238:241], v[74:77]
	v_mfma_f32_16x16x32_bf16 v[126:129], v[174:177], v[206:209], v[126:129]
	v_mfma_f32_16x16x32_bf16 v[122:125], v[182:185], v[206:209], v[122:125]
	v_mfma_f32_16x16x32_bf16 v[110:113], v[174:177], v[226:229], v[110:113]
	v_mfma_f32_16x16x32_bf16 v[106:109], v[182:185], v[226:229], v[106:109]
	v_mfma_f32_16x16x32_bf16 v[94:97], v[174:177], v[234:237], v[94:97]
	v_mfma_f32_16x16x32_bf16 v[90:93], v[182:185], v[234:237], v[90:93]
	v_mfma_f32_16x16x32_bf16 v[78:81], v[174:177], v[242:245], v[78:81]
	v_mfma_f32_16x16x32_bf16 v[74:77], v[182:185], v[242:245], v[74:77]
	s_setprio 0
	s_setprio 1
	v_mfma_f32_16x16x32_bf16 v[118:121], v[186:189], v[202:205], v[118:121]
	v_mfma_f32_16x16x32_bf16 v[114:117], v[194:197], v[202:205], v[114:117]
	v_mfma_f32_16x16x32_bf16 v[102:105], v[186:189], v[222:225], v[102:105]
	v_mfma_f32_16x16x32_bf16 v[98:101], v[194:197], v[222:225], v[98:101]
	v_mfma_f32_16x16x32_bf16 v[86:89], v[186:189], v[230:233], v[86:89]
	v_mfma_f32_16x16x32_bf16 v[82:85], v[194:197], v[230:233], v[82:85]
	v_mfma_f32_16x16x32_bf16 v[70:73], v[186:189], v[238:241], v[70:73]
	v_mfma_f32_16x16x32_bf16 v[66:69], v[194:197], v[238:241], v[66:69]
	v_mfma_f32_16x16x32_bf16 v[118:121], v[190:193], v[206:209], v[118:121]
	v_mfma_f32_16x16x32_bf16 v[114:117], v[198:201], v[206:209], v[114:117]
	v_mfma_f32_16x16x32_bf16 v[102:105], v[190:193], v[226:229], v[102:105]
	v_mfma_f32_16x16x32_bf16 v[98:101], v[198:201], v[226:229], v[98:101]
	v_mfma_f32_16x16x32_bf16 v[86:89], v[190:193], v[234:237], v[86:89]
	v_mfma_f32_16x16x32_bf16 v[82:85], v[198:201], v[234:237], v[82:85]
	v_mfma_f32_16x16x32_bf16 v[70:73], v[190:193], v[242:245], v[70:73]
	v_mfma_f32_16x16x32_bf16 v[66:69], v[198:201], v[242:245], v[66:69]
	s_setprio 0
	s_barrier
	s_add_i32 s92, s92, s84
	v_lshl_add_u64 v[210:211], s[70:71], 0, v[132:133]
	s_mov_b32 m0, s92
	ds_read_b128 v[202:205], v171 offset:16384
	ds_read_b128 v[206:209], v171 offset:17408
	ds_read_b128 v[222:225], v171 offset:18432
	ds_read_b128 v[226:229], v171 offset:19456
	ds_read_b128 v[230:233], v171 offset:20480
	ds_read_b128 v[234:237], v171 offset:21504
	ds_read_b128 v[238:241], v171 offset:22528
	ds_read_b128 v[242:245], v171 offset:23552
	global_load_lds_dwordx4 v[210:211], off
	s_add_i32 m0, s92, 0x2000
	s_add_u32 s92, s70, 0x80000
	v_lshl_add_u64 v[216:217], s[70:71], 0, v[130:131]
	s_addc_u32 s93, s71, 0
	s_add_i32 s94, s94, s84
	global_load_lds_dwordx4 v[216:217], off
	v_lshl_add_u64 v[246:247], s[92:93], 0, v[132:133]
	s_mov_b32 m0, s94
	v_lshl_add_u64 v[248:249], s[72:73], 0, v[130:131]
	global_load_lds_dwordx4 v[246:247], off
	v_lshl_add_u64 v[246:247], s[92:93], 0, v[130:131]
	s_add_i32 m0, s94, 0x2000
	s_nop 0
	global_load_lds_dwordx4 v[246:247], off
	v_lshl_add_u64 v[246:247], s[72:73], 0, v[132:133]
	s_waitcnt vmcnt(6)
	s_waitcnt lgkmcnt(0)
	s_barrier
; #define PG8_STAGE(bufoff, gbase) do { _Pragma("unroll") for (int _i = 0; _i < 2; ++_i) \
;         __builtin_amdgcn_global_load_lds((const unsigned*)((const char*)(gbase) + voffA[_i]), (LAS unsigned*)(lds + (bufoff) + ldsw + _i * 8192), 16, 0, 0); } while (0)
; #define PG8_LDA(dst, b, h) do { _Pragma("unroll") for (int m = 0; m < 4; ++m) _Pragma("unroll") for (int k = 0; k < 2; ++k) dst[m][k] = *(const LAS bf16x8*)(lds + PG8_SA(b, h) + aoff + m * 2048 + k * 1024); } while (0)
; #define PG8_LDB(dst, b, h) do { _Pragma("unroll") for (int n = 0; n < 2; ++n) _Pragma("unroll") for (int k = 0; k < 2; ++k) dst[n][k] = *(const LAS bf16x8*)(lds + PG8_SB(b, h) + boff + n * 2048 + k * 1024); } while (0)
; #define PG8_MMA(ai, bj, At, Bt) do { __builtin_amdgcn_s_setprio(1); _Pragma("unroll") for (int m = 0; m < 4; ++m) _Pragma("unroll") for (int n = 0; n < 2; ++n) _Pragma("unroll") for (int k = 0; k < 2; ++k) \
;         acc[ai][bj][m][n] = __builtin_amdgcn_mfma_f32_16x16x32_bf16(Bt[n][k], At[m][k], acc[ai][bj][m][n], 0, 0, 0); __builtin_amdgcn_s_setprio(0); } while (0)
; #define PG8_WAIT_V(n) asm volatile("s_waitcnt vmcnt(" #n ")" ::: "memory")
; #define PG8_WAIT_L(n) asm volatile("s_waitcnt lgkmcnt(" #n ")" ::: "memory")
; #define PG8_BAR __builtin_amdgcn_s_barrier()
; #define PG8_SCHED __builtin_amdgcn_sched_barrier(0)
; template <class Epi, class Sched>
; __device__ __forceinline__ void gemm_phase(LAS unsigned char* lds, const Gemm g, const Sched& S, const Epi& E) {
;     ...
;             PG8_WAIT_V(8); PG8_WAIT_L(0); PG8_BAR; PG8_MMA(0, 0, At, B0); PG8_MMA(0, 1, At, B1); PG8_BAR; PG8_SCHED;
;             PG8_LDA(At, 0, 1); PG8_STAGE(PG8_SB(0, 0), b2); PG8_STAGE(PG8_SB(0, 1), b2 + hstep); PG8_STAGE(PG8_SA(0, 0), a2);
;             PG8_WAIT_V(8); PG8_WAIT_L(0); PG8_BAR; PG8_MMA(1, 0, At, B0); PG8_MMA(1, 1, At, B1); PG8_BAR; PG8_SCHED;
;             PG8_LDB(B0, 1, 0); PG8_LDB(B1, 1, 1); PG8_SCHED; PG8_LDA(At, 1, 0); PG8_STAGE(PG8_SA(0, 1), a2 + hstep);
;             PG8_WAIT_V(8); PG8_WAIT_L(0); PG8_BAR; PG8_MMA(0, 0, At, B0); PG8_MMA(0, 1, At, B1); PG8_BAR; PG8_SCHED;
	s_setprio 1
	s_waitcnt lgkmcnt(0)
	v_mfma_f32_16x16x32_bf16 v[62:65], v[166:169], v[202:205], v[62:65]
	v_mfma_f32_16x16x32_bf16 v[58:61], v[178:181], v[202:205], v[58:61]
	v_mfma_f32_16x16x32_bf16 v[46:49], v[166:169], v[222:225], v[46:49]
	v_mfma_f32_16x16x32_bf16 v[42:45], v[178:181], v[222:225], v[42:45]
	v_mfma_f32_16x16x32_bf16 v[30:33], v[166:169], v[230:233], v[30:33]
	v_mfma_f32_16x16x32_bf16 v[26:29], v[178:181], v[230:233], v[26:29]
	v_mfma_f32_16x16x32_bf16 v[14:17], v[166:169], v[238:241], v[14:17]
	v_mfma_f32_16x16x32_bf16 v[10:13], v[178:181], v[238:241], v[10:13]
	v_mfma_f32_16x16x32_bf16 v[62:65], v[174:177], v[206:209], v[62:65]
	v_mfma_f32_16x16x32_bf16 v[58:61], v[182:185], v[206:209], v[58:61]
	v_mfma_f32_16x16x32_bf16 v[46:49], v[174:177], v[226:229], v[46:49]
	v_mfma_f32_16x16x32_bf16 v[42:45], v[182:185], v[226:229], v[42:45]
	v_mfma_f32_16x16x32_bf16 v[30:33], v[174:177], v[234:237], v[30:33]
	v_mfma_f32_16x16x32_bf16 v[26:29], v[182:185], v[234:237], v[26:29]
	v_mfma_f32_16x16x32_bf16 v[14:17], v[174:177], v[242:245], v[14:17]
	v_mfma_f32_16x16x32_bf16 v[10:13], v[182:185], v[242:245], v[10:13]
	s_setprio 0
	s_setprio 1
	v_mfma_f32_16x16x32_bf16 v[54:57], v[186:189], v[202:205], v[54:57]
	v_mfma_f32_16x16x32_bf16 v[50:53], v[194:197], v[202:205], v[50:53]
	v_mfma_f32_16x16x32_bf16 v[38:41], v[186:189], v[222:225], v[38:41]
	v_mfma_f32_16x16x32_bf16 v[34:37], v[194:197], v[222:225], v[34:37]
	v_mfma_f32_16x16x32_bf16 v[22:25], v[186:189], v[230:233], v[22:25]
	v_mfma_f32_16x16x32_bf16 v[18:21], v[194:197], v[230:233], v[18:21]
	v_mfma_f32_16x16x32_bf16 v[6:9], v[186:189], v[238:241], v[6:9]
	v_mfma_f32_16x16x32_bf16 v[2:5], v[194:197], v[238:241], v[2:5]
	v_mfma_f32_16x16x32_bf16 v[54:57], v[190:193], v[206:209], v[54:57]
	v_mfma_f32_16x16x32_bf16 v[50:53], v[198:201], v[206:209], v[50:53]
	v_mfma_f32_16x16x32_bf16 v[38:41], v[190:193], v[226:229], v[38:41]
	v_mfma_f32_16x16x32_bf16 v[34:37], v[198:201], v[226:229], v[34:37]
	v_mfma_f32_16x16x32_bf16 v[22:25], v[190:193], v[234:237], v[22:25]
	v_mfma_f32_16x16x32_bf16 v[18:21], v[198:201], v[234:237], v[18:21]
	v_mfma_f32_16x16x32_bf16 v[6:9], v[190:193], v[242:245], v[6:9]
	v_mfma_f32_16x16x32_bf16 v[2:5], v[198:201], v[242:245], v[2:5]
	s_setprio 0
	s_barrier
	v_add_u32_e32 v0, s99, v170
	s_add_i32 s92, 0, 0x1c000
	ds_read_b128 v[166:169], v0
	ds_read_b128 v[174:177], v0 offset:1024
	ds_read_b128 v[178:181], v0 offset:2048
	ds_read_b128 v[182:185], v0 offset:3072
	v_add_u32_e32 v0, s92, v170
	ds_read_b128 v[186:189], v0
	ds_read_b128 v[190:193], v0 offset:1024
	ds_read_b128 v[194:197], v0 offset:2048
	ds_read_b128 v[198:201], v0 offset:3072
	s_add_u32 s72, s72, 0x80000
	s_addc_u32 s73, s73, 0
	s_mov_b32 m0, s44
	v_lshl_add_u64 v[250:251], s[72:73], 0, v[132:133]
	ds_read_b128 v[202:205], v171 offset:32768
	ds_read_b128 v[206:209], v171 offset:33792
	ds_read_b128 v[222:225], v171 offset:34816
	ds_read_b128 v[226:229], v171 offset:35840
	ds_read_b128 v[230:233], v171 offset:36864
	ds_read_b128 v[234:237], v171 offset:37888
	ds_read_b128 v[238:241], v171 offset:38912
	ds_read_b128 v[242:245], v171 offset:39936
	global_load_lds_dwordx4 v[250:251], off
	v_lshl_add_u64 v[250:251], s[72:73], 0, v[130:131]
	s_mov_b32 m0, s45
	s_nop 0
	global_load_lds_dwordx4 v[250:251], off
	s_mov_b32 m0, s60
	s_nop 0
	global_load_lds_dwordx4 v[246:247], off
	s_mov_b32 m0, s61
	s_nop 0
	global_load_lds_dwordx4 v[248:249], off
	s_waitcnt vmcnt(8)
	s_waitcnt lgkmcnt(0)
	s_barrier
	s_setprio 1
	s_waitcnt lgkmcnt(0)
	v_mfma_f32_16x16x32_bf16 v[126:129], v[166:169], v[202:205], v[126:129]
	v_mfma_f32_16x16x32_bf16 v[122:125], v[178:181], v[202:205], v[122:125]
	v_mfma_f32_16x16x32_bf16 v[110:113], v[166:169], v[222:225], v[110:113]
	v_mfma_f32_16x16x32_bf16 v[106:109], v[178:181], v[222:225], v[106:109]
	v_mfma_f32_16x16x32_bf16 v[94:97], v[166:169], v[230:233], v[94:97]
	v_mfma_f32_16x16x32_bf16 v[90:93], v[178:181], v[230:233], v[90:93]
	v_mfma_f32_16x16x32_bf16 v[78:81], v[166:169], v[238:241], v[78:81]
	v_mfma_f32_16x16x32_bf16 v[74:77], v[178:181], v[238:241], v[74:77]
	v_mfma_f32_16x16x32_bf16 v[126:129], v[174:177], v[206:209], v[126:129]
	v_mfma_f32_16x16x32_bf16 v[122:125], v[182:185], v[206:209], v[122:125]
	v_mfma_f32_16x16x32_bf16 v[110:113], v[174:177], v[226:229], v[110:113]
	v_mfma_f32_16x16x32_bf16 v[106:109], v[182:185], v[226:229], v[106:109]
	v_mfma_f32_16x16x32_bf16 v[94:97], v[174:177], v[234:237], v[94:97]
	v_mfma_f32_16x16x32_bf16 v[90:93], v[182:185], v[234:237], v[90:93]
	v_mfma_f32_16x16x32_bf16 v[78:81], v[174:177], v[242:245], v[78:81]
	v_mfma_f32_16x16x32_bf16 v[74:77], v[182:185], v[242:245], v[74:77]
	s_setprio 0
	s_setprio 1
	v_mfma_f32_16x16x32_bf16 v[118:121], v[186:189], v[202:205], v[118:121]
	v_mfma_f32_16x16x32_bf16 v[114:117], v[194:197], v[202:205], v[114:117]
	v_mfma_f32_16x16x32_bf16 v[102:105], v[186:189], v[222:225], v[102:105]
	v_mfma_f32_16x16x32_bf16 v[98:101], v[194:197], v[222:225], v[98:101]
	v_mfma_f32_16x16x32_bf16 v[86:89], v[186:189], v[230:233], v[86:89]
	v_mfma_f32_16x16x32_bf16 v[82:85], v[194:197], v[230:233], v[82:85]
	v_mfma_f32_16x16x32_bf16 v[70:73], v[186:189], v[238:241], v[70:73]
	v_mfma_f32_16x16x32_bf16 v[66:69], v[194:197], v[238:241], v[66:69]
	v_mfma_f32_16x16x32_bf16 v[118:121], v[190:193], v[206:209], v[118:121]
	v_mfma_f32_16x16x32_bf16 v[114:117], v[198:201], v[206:209], v[114:117]
	v_mfma_f32_16x16x32_bf16 v[102:105], v[190:193], v[226:229], v[102:105]
	v_mfma_f32_16x16x32_bf16 v[98:101], v[198:201], v[226:229], v[98:101]
	v_mfma_f32_16x16x32_bf16 v[86:89], v[190:193], v[234:237], v[86:89]
	v_mfma_f32_16x16x32_bf16 v[82:85], v[198:201], v[234:237], v[82:85]
	v_mfma_f32_16x16x32_bf16 v[70:73], v[190:193], v[242:245], v[70:73]
	v_mfma_f32_16x16x32_bf16 v[66:69], v[198:201], v[242:245], v[66:69]
	s_setprio 0
	s_barrier
; #define PG8_STAGE(bufoff, gbase) do { _Pragma("unroll") for (int _i = 0; _i < 2; ++_i) \
;         __builtin_amdgcn_global_load_lds((const unsigned*)((const char*)(gbase) + voffA[_i]), (LAS unsigned*)(lds + (bufoff) + ldsw + _i * 8192), 16, 0, 0); } while (0)
; #define PG8_LDA(dst, b, h) do { _Pragma("unroll") for (int m = 0; m < 4; ++m) _Pragma("unroll") for (int k = 0; k < 2; ++k) dst[m][k] = *(const LAS bf16x8*)(lds + PG8_SA(b, h) + aoff + m * 2048 + k * 1024); } while (0)
; #define PG8_MMA(ai, bj, At, Bt) do { __builtin_amdgcn_s_setprio(1); _Pragma("unroll") for (int m = 0; m < 4; ++m) _Pragma("unroll") for (int n = 0; n < 2; ++n) _Pragma("unroll") for (int k = 0; k < 2; ++k) \
;         acc[ai][bj][m][n] = __builtin_amdgcn_mfma_f32_16x16x32_bf16(Bt[n][k], At[m][k], acc[ai][bj][m][n], 0, 0, 0); __builtin_amdgcn_s_setprio(0); } while (0)
; #define PG8_WAIT_V(n) asm volatile("s_waitcnt vmcnt(" #n ")" ::: "memory")
; #define PG8_WAIT_L(n) asm volatile("s_waitcnt lgkmcnt(" #n ")" ::: "memory")
; #define PG8_BAR __builtin_amdgcn_s_barrier()
; #define PG8_SCHED __builtin_amdgcn_sched_barrier(0)
; template <class Epi, class Sched>
; __device__ __forceinline__ void gemm_phase(LAS unsigned char* lds, const Gemm g, const Sched& S, const Epi& E) {
;     ...
;             PG8_LDA(At, 1, 1); PG8_STAGE(PG8_SB(1, 0), b3); PG8_STAGE(PG8_SB(1, 1), b3 + hstep); PG8_STAGE(PG8_SA(1, 0), a3);
;             PG8_WAIT_V(8); PG8_WAIT_L(0); PG8_BAR; PG8_MMA(1, 0, At, B0); PG8_MMA(1, 1, At, B1); PG8_BAR; PG8_SCHED;
;         }
	s_add_i32 s72, s99, s84
	v_lshl_add_u64 v[210:211], v[210:211], 0, s[26:27]
	s_mov_b32 m0, s72
	ds_read_b128 v[202:205], v171 offset:49152
	ds_read_b128 v[206:209], v171 offset:50176
	ds_read_b128 v[222:225], v171 offset:51200
	ds_read_b128 v[226:229], v171 offset:52224
	ds_read_b128 v[230:233], v171 offset:53248
	ds_read_b128 v[234:237], v171 offset:54272
	ds_read_b128 v[238:241], v171 offset:55296
	ds_read_b128 v[242:245], v171 offset:56320
	global_load_lds_dwordx4 v[210:211], off
	s_add_i32 m0, s72, 0x2000
	s_add_u32 s70, s70, 0x80080
	v_lshl_add_u64 v[210:211], v[216:217], 0, s[26:27]
	s_addc_u32 s71, s71, 0
	s_add_i32 s72, s92, s84
	global_load_lds_dwordx4 v[210:211], off
	v_lshl_add_u64 v[210:211], s[70:71], 0, v[132:133]
	s_mov_b32 m0, s72
	s_nop 0
	global_load_lds_dwordx4 v[210:211], off
	v_lshl_add_u64 v[210:211], s[70:71], 0, v[130:131]
	s_add_i32 m0, s72, 0x2000
	s_nop 0
	global_load_lds_dwordx4 v[210:211], off
	v_lshl_add_u64 v[210:211], v[246:247], 0, s[26:27]
	s_mov_b32 m0, s38
	s_nop 0
	global_load_lds_dwordx4 v[210:211], off
	v_lshl_add_u64 v[210:211], v[248:249], 0, s[26:27]
	s_mov_b32 m0, s39
	s_nop 0
	global_load_lds_dwordx4 v[210:211], off
	s_waitcnt vmcnt(6)
	s_waitcnt lgkmcnt(0)
	s_barrier
	s_setprio 1
	s_waitcnt lgkmcnt(0)
	v_mfma_f32_16x16x32_bf16 v[62:65], v[166:169], v[202:205], v[62:65]
	v_mfma_f32_16x16x32_bf16 v[58:61], v[178:181], v[202:205], v[58:61]
	v_mfma_f32_16x16x32_bf16 v[46:49], v[166:169], v[222:225], v[46:49]
	v_mfma_f32_16x16x32_bf16 v[42:45], v[178:181], v[222:225], v[42:45]
	v_mfma_f32_16x16x32_bf16 v[30:33], v[166:169], v[230:233], v[30:33]
	v_mfma_f32_16x16x32_bf16 v[26:29], v[178:181], v[230:233], v[26:29]
	v_mfma_f32_16x16x32_bf16 v[14:17], v[166:169], v[238:241], v[14:17]
	v_mfma_f32_16x16x32_bf16 v[10:13], v[178:181], v[238:241], v[10:13]
	v_mfma_f32_16x16x32_bf16 v[62:65], v[174:177], v[206:209], v[62:65]
	v_mfma_f32_16x16x32_bf16 v[58:61], v[182:185], v[206:209], v[58:61]
	v_mfma_f32_16x16x32_bf16 v[46:49], v[174:177], v[226:229], v[46:49]
	v_mfma_f32_16x16x32_bf16 v[42:45], v[182:185], v[226:229], v[42:45]
	v_mfma_f32_16x16x32_bf16 v[30:33], v[174:177], v[234:237], v[30:33]
	v_mfma_f32_16x16x32_bf16 v[26:29], v[182:185], v[234:237], v[26:29]
	v_mfma_f32_16x16x32_bf16 v[14:17], v[174:177], v[242:245], v[14:17]
	v_mfma_f32_16x16x32_bf16 v[10:13], v[182:185], v[242:245], v[10:13]
	s_setprio 0
	s_setprio 1
	v_mfma_f32_16x16x32_bf16 v[54:57], v[186:189], v[202:205], v[54:57]
	v_mfma_f32_16x16x32_bf16 v[50:53], v[194:197], v[202:205], v[50:53]
	v_mfma_f32_16x16x32_bf16 v[38:41], v[186:189], v[222:225], v[38:41]
	v_mfma_f32_16x16x32_bf16 v[34:37], v[194:197], v[222:225], v[34:37]
	v_mfma_f32_16x16x32_bf16 v[22:25], v[186:189], v[230:233], v[22:25]
	v_mfma_f32_16x16x32_bf16 v[18:21], v[194:197], v[230:233], v[18:21]
	v_mfma_f32_16x16x32_bf16 v[6:9], v[186:189], v[238:241], v[6:9]
	v_mfma_f32_16x16x32_bf16 v[2:5], v[194:197], v[238:241], v[2:5]
	v_mfma_f32_16x16x32_bf16 v[54:57], v[190:193], v[206:209], v[54:57]
	v_mfma_f32_16x16x32_bf16 v[50:53], v[198:201], v[206:209], v[50:53]
	v_mfma_f32_16x16x32_bf16 v[38:41], v[190:193], v[226:229], v[38:41]
	v_mfma_f32_16x16x32_bf16 v[34:37], v[198:201], v[226:229], v[34:37]
	v_mfma_f32_16x16x32_bf16 v[22:25], v[190:193], v[234:237], v[22:25]
	v_mfma_f32_16x16x32_bf16 v[18:21], v[198:201], v[234:237], v[18:21]
	v_mfma_f32_16x16x32_bf16 v[6:9], v[190:193], v[242:245], v[6:9]
	v_mfma_f32_16x16x32_bf16 v[2:5], v[198:201], v[242:245], v[2:5]
	s_setprio 0
	s_barrier
	s_add_i32 s91, s91, 2
	s_add_u32 s68, s68, 0x100
	s_addc_u32 s69, s69, 0
	s_add_u32 s89, s89, 0x100
	s_addc_u32 s90, s90, 0
	s_cmp_gt_u32 s91, 29
	s_cbranch_scc0 .LBB0_156
	s_and_b64 vcc, exec, s[46:47]
	s_cbranch_vccz .LBB0_159
	s_barrier
